# prologue-B LayerNorm loop hand-rewritten: SGPR addressing, next-row prefetch, 8 modulation loads issued at trip top
# speedup vs baseline: 1.0285x; 1.0285x over previous
.LBB0_157:
	s_or_b64 exec, exec, s[0:1]
	v_mov_b32_e32 v0, v170
	s_lshl_b32 s71, s80, 3
	v_readlane_b32 s0, v253, 0
	v_ashrrev_i32_e32 v1, 6, v0
	v_add_u32_e32 v16, s71, v1
	s_movk_i32 s0, 0x4200
	s_lshl_b32 s72, s96, 3
	v_readlane_b32 s2, v253, 2
	v_readlane_b32 s3, v253, 3
	v_cmp_gt_i32_e32 vcc, s0, v16
	v_mbcnt_lo_u32_b32 v28, -1, 0
	v_readlane_b32 s1, v253, 1
	s_and_saveexec_b64 s[4:5], vcc
	s_cbranch_execz .LBB0_164
	v_mbcnt_hi_u32_b32 v1, -1, v28
	v_lshlrev_b32_e32 v18, 4, v1
	v_lshlrev_b32_e32 v19, 3, v1
	v_xor_b32_e32 v3, 32, v1
	v_lshlrev_b32_e32 v29, 2, v3
	v_xor_b32_e32 v3, 16, v1
	v_lshlrev_b32_e32 v30, 2, v3
	v_xor_b32_e32 v3, 8, v1
	v_lshlrev_b32_e32 v31, 2, v3
	v_xor_b32_e32 v3, 4, v1
	v_lshlrev_b32_e32 v32, 2, v3
	v_xor_b32_e32 v3, 2, v1
	v_lshlrev_b32_e32 v33, 2, v3
	v_xor_b32_e32 v3, 1, v1
	v_lshlrev_b32_e32 v34, 2, v3
	v_mov_b32_e32 v36, 0x3727c5ac
	v_mov_b32_e32 v37, 0x260
	s_mov_b32 s7, 0xf800000
	v_readfirstlane_b32 s6, v16
	s_cmp_ge_u32 s6, 0x2100
	s_cselect_b32 s12, 1, 0
	s_mul_i32 s13, s12, 0x2100
	s_sub_u32 s13, s6, s13
	s_lshl_b32 s14, s12, 13
	s_add_u32 s14, s14, s13
	s_lshl_b32 s8, s12, 8
	s_add_u32 s8, s8, s13
	s_sub_u32 s8, s8, 0x2000
	s_cmp_lt_u32 s13, 0x2000
	s_cselect_b32 s14, s14, s8
	s_cselect_b32 s15, s12, 2
	s_cselect_b32 s8, s52, s56
	s_cselect_b32 s9, s53, s57
	s_lshl_b32 s14, s14, 12
	s_add_u32 s8, s8, s14
	s_addc_u32 s9, s9, 0
	global_load_dwordx4 v[64:67], v18, s[8:9]
	global_load_dwordx4 v[68:71], v18, s[8:9] offset:1024
	global_load_dwordx4 v[72:75], v18, s[8:9] offset:2048
	global_load_dwordx4 v[76:79], v18, s[8:9] offset:3072
.Lpb_loop:
	s_add_u32 s10, s6, s72
	s_cmp_lt_u32 s10, 0x4200
	s_cbranch_scc0 .Lpb_last_a
	s_mul_i32 s12, s15, 0x3000
	s_add_u32 s16, s2, s12
	s_addc_u32 s17, s3, 0
	s_add_u32 s0, s16, 0x1000
	s_addc_u32 s1, s17, 0
	global_load_dwordx4 v[96:99], v18, s[16:17]
	global_load_dwordx4 v[100:103], v18, s[16:17] offset:1024
	global_load_dwordx4 v[104:107], v18, s[16:17] offset:2048
	global_load_dwordx4 v[108:111], v18, s[16:17] offset:3072
	global_load_dwordx4 v[112:115], v18, s[0:1]
	global_load_dwordx4 v[116:119], v18, s[0:1] offset:1024
	global_load_dwordx4 v[120:123], v18, s[0:1] offset:2048
	global_load_dwordx4 v[124:127], v18, s[0:1] offset:3072
	s_cmp_ge_u32 s10, 0x2100
	s_cselect_b32 s12, 1, 0
	s_mul_i32 s13, s12, 0x2100
	s_sub_u32 s13, s10, s13
	s_lshl_b32 s14, s12, 13
	s_add_u32 s14, s14, s13
	s_lshl_b32 s8, s12, 8
	s_add_u32 s8, s8, s13
	s_sub_u32 s8, s8, 0x2000
	s_cmp_lt_u32 s13, 0x2000
	s_cselect_b32 s14, s14, s8
	s_cselect_b32 s11, s12, 2
	s_cselect_b32 s8, s52, s56
	s_cselect_b32 s9, s53, s57
	s_lshl_b32 s14, s14, 12
	s_add_u32 s8, s8, s14
	s_addc_u32 s9, s9, 0
	global_load_dwordx4 v[80:83], v18, s[8:9]
	global_load_dwordx4 v[84:87], v18, s[8:9] offset:1024
	global_load_dwordx4 v[88:91], v18, s[8:9] offset:2048
	global_load_dwordx4 v[92:95], v18, s[8:9] offset:3072
	s_waitcnt vmcnt(12)
	v_add_f32_e32 v38, v64, v65
	v_add_f32_e32 v39, v66, v67
	v_add_f32_e32 v40, v68, v69
	v_add_f32_e32 v41, v70, v71
	v_add_f32_e32 v42, v72, v73
	v_add_f32_e32 v43, v74, v75
	v_add_f32_e32 v44, v76, v77
	v_add_f32_e32 v45, v78, v79
	v_add_f32_e32 v38, v38, v39
	v_add_f32_e32 v40, v40, v41
	v_add_f32_e32 v42, v42, v43
	v_add_f32_e32 v44, v44, v45
	v_add_f32_e32 v38, v38, v40
	v_add_f32_e32 v38, v38, v42
	v_add_f32_e32 v38, v38, v44
	ds_bpermute_b32 v46, v29, v38
	s_waitcnt lgkmcnt(0)
	v_add_f32_e32 v38, v38, v46
	ds_bpermute_b32 v46, v30, v38
	s_waitcnt lgkmcnt(0)
	v_add_f32_e32 v38, v38, v46
	ds_bpermute_b32 v46, v31, v38
	s_waitcnt lgkmcnt(0)
	v_add_f32_e32 v38, v38, v46
	ds_bpermute_b32 v46, v32, v38
	s_waitcnt lgkmcnt(0)
	v_add_f32_e32 v38, v38, v46
	ds_bpermute_b32 v46, v33, v38
	s_waitcnt lgkmcnt(0)
	v_add_f32_e32 v38, v38, v46
	ds_bpermute_b32 v46, v34, v38
	s_waitcnt lgkmcnt(0)
	v_add_f32_e32 v38, v38, v46
	v_fmamk_f32 v0, v38, 0xba800000, v64
	v_fmamk_f32 v1, v38, 0xba800000, v65
	v_fmamk_f32 v2, v38, 0xba800000, v66
	v_fmamk_f32 v3, v38, 0xba800000, v67
	v_fmamk_f32 v4, v38, 0xba800000, v68
	v_fmamk_f32 v5, v38, 0xba800000, v69
	v_fmamk_f32 v6, v38, 0xba800000, v70
	v_fmamk_f32 v7, v38, 0xba800000, v71
	v_fmamk_f32 v8, v38, 0xba800000, v72
	v_fmamk_f32 v9, v38, 0xba800000, v73
	v_fmamk_f32 v10, v38, 0xba800000, v74
	v_fmamk_f32 v11, v38, 0xba800000, v75
	v_fmamk_f32 v12, v38, 0xba800000, v76
	v_fmamk_f32 v13, v38, 0xba800000, v77
	v_fmamk_f32 v14, v38, 0xba800000, v78
	v_fmamk_f32 v15, v38, 0xba800000, v79
	v_mul_f32_e32 v38, v0, v0
	v_mul_f32_e32 v39, v2, v2
	v_mul_f32_e32 v40, v4, v4
	v_mul_f32_e32 v41, v6, v6
	v_mul_f32_e32 v42, v8, v8
	v_mul_f32_e32 v43, v10, v10
	v_mul_f32_e32 v44, v12, v12
	v_mul_f32_e32 v45, v14, v14
	v_fmac_f32_e32 v38, v1, v1
	v_fmac_f32_e32 v39, v3, v3
	v_fmac_f32_e32 v40, v5, v5
	v_fmac_f32_e32 v41, v7, v7
	v_fmac_f32_e32 v42, v9, v9
	v_fmac_f32_e32 v43, v11, v11
	v_fmac_f32_e32 v44, v13, v13
	v_fmac_f32_e32 v45, v15, v15
	v_add_f32_e32 v38, v38, v39
	v_add_f32_e32 v40, v40, v41
	v_add_f32_e32 v42, v42, v43
	v_add_f32_e32 v44, v44, v45
	v_add_f32_e32 v38, v38, v40
	v_add_f32_e32 v38, v38, v42
	v_add_f32_e32 v38, v38, v44
	ds_bpermute_b32 v46, v29, v38
	s_waitcnt lgkmcnt(0)
	v_add_f32_e32 v38, v38, v46
	ds_bpermute_b32 v46, v30, v38
	s_waitcnt lgkmcnt(0)
	v_add_f32_e32 v38, v38, v46
	ds_bpermute_b32 v46, v31, v38
	s_waitcnt lgkmcnt(0)
	v_add_f32_e32 v38, v38, v46
	ds_bpermute_b32 v46, v32, v38
	s_waitcnt lgkmcnt(0)
	v_add_f32_e32 v38, v38, v46
	ds_bpermute_b32 v46, v33, v38
	s_waitcnt lgkmcnt(0)
	v_add_f32_e32 v38, v38, v46
	ds_bpermute_b32 v46, v34, v38
	s_waitcnt lgkmcnt(0)
	v_add_f32_e32 v38, v38, v46
	v_fmamk_f32 v56, v38, 0x3a800000, v36
	v_mul_f32_e32 v57, 0x4f800000, v56
	v_cmp_gt_f32_e32 vcc, s7, v56
	s_nop 1
	v_cndmask_b32_e32 v58, v56, v57, vcc
	v_sqrt_f32_e32 v59, v58
	s_nop 0
	v_add_u32_e32 v60, -1, v59
	v_add_u32_e32 v61, 1, v59
	v_fma_f32 v62, -v60, v59, v58
	v_fma_f32 v63, -v61, v59, v58
	v_cmp_ge_f32_e64 s[12:13], 0, v62
	s_nop 1
	v_cndmask_b32_e64 v60, v59, v60, s[12:13]
	v_cmp_lt_f32_e64 s[12:13], 0, v63
	s_nop 1
	v_cndmask_b32_e64 v60, v60, v61, s[12:13]
	v_mul_f32_e32 v61, 0x37800000, v60
	v_cndmask_b32_e32 v60, v60, v61, vcc
	v_cmp_class_f32_e32 vcc, v58, v37
	s_nop 1
	v_cndmask_b32_e32 v58, v60, v58, vcc
	v_div_scale_f32 v60, s[12:13], v58, v58, 1.0
	v_rcp_f32_e32 v61, v60
	v_div_scale_f32 v59, vcc, 1.0, v58, 1.0
	v_fma_f32 v62, -v60, v61, 1.0
	v_fmac_f32_e32 v61, v62, v61
	v_mul_f32_e32 v62, v59, v61
	v_fma_f32 v63, -v60, v62, v59
	v_fmac_f32_e32 v62, v63, v61
	v_fma_f32 v60, -v60, v62, v59
	v_div_fmas_f32 v60, v60, v61, v62
	v_div_fixup_f32 v60, v60, v58, 1.0
	s_lshl_b32 s12, s6, 11
	s_add_u32 s12, s2, s12
	s_addc_u32 s13, s3, 0
	s_add_u32 s12, s12, 0x5b00000
	s_addc_u32 s13, s13, 0
	v_mul_f32_e32 v0, v0, v60
	v_mul_f32_e32 v1, v1, v60
	v_mul_f32_e32 v2, v2, v60
	v_mul_f32_e32 v3, v3, v60
	v_mul_f32_e32 v4, v4, v60
	v_mul_f32_e32 v5, v5, v60
	v_mul_f32_e32 v6, v6, v60
	v_mul_f32_e32 v7, v7, v60
	v_mul_f32_e32 v8, v8, v60
	v_mul_f32_e32 v9, v9, v60
	v_mul_f32_e32 v10, v10, v60
	v_mul_f32_e32 v11, v11, v60
	v_mul_f32_e32 v12, v12, v60
	v_mul_f32_e32 v13, v13, v60
	v_mul_f32_e32 v14, v14, v60
	v_mul_f32_e32 v15, v15, v60
	s_waitcnt vmcnt(4)
	v_add_f32_e32 v112, 1.0, v112
	v_add_f32_e32 v113, 1.0, v113
	v_add_f32_e32 v114, 1.0, v114
	v_add_f32_e32 v115, 1.0, v115
	v_add_f32_e32 v116, 1.0, v116
	v_add_f32_e32 v117, 1.0, v117
	v_add_f32_e32 v118, 1.0, v118
	v_add_f32_e32 v119, 1.0, v119
	v_add_f32_e32 v120, 1.0, v120
	v_add_f32_e32 v121, 1.0, v121
	v_add_f32_e32 v122, 1.0, v122
	v_add_f32_e32 v123, 1.0, v123
	v_add_f32_e32 v124, 1.0, v124
	v_add_f32_e32 v125, 1.0, v125
	v_add_f32_e32 v126, 1.0, v126
	v_add_f32_e32 v127, 1.0, v127
	v_fma_f32 v0, v0, v112, v96
	v_fma_f32 v1, v1, v113, v97
	v_fma_f32 v2, v2, v114, v98
	v_fma_f32 v3, v3, v115, v99
	v_fma_f32 v4, v4, v116, v100
	v_fma_f32 v5, v5, v117, v101
	v_fma_f32 v6, v6, v118, v102
	v_fma_f32 v7, v7, v119, v103
	v_fma_f32 v8, v8, v120, v104
	v_fma_f32 v9, v9, v121, v105
	v_fma_f32 v10, v10, v122, v106
	v_fma_f32 v11, v11, v123, v107
	v_fma_f32 v12, v12, v124, v108
	v_fma_f32 v13, v13, v125, v109
	v_fma_f32 v14, v14, v126, v110
	v_fma_f32 v15, v15, v127, v111
	v_cvt_pk_bf16_f32 v48, v0, v1
	v_cvt_pk_bf16_f32 v49, v2, v3
	v_cvt_pk_bf16_f32 v50, v4, v5
	v_cvt_pk_bf16_f32 v51, v6, v7
	v_cvt_pk_bf16_f32 v52, v8, v9
	v_cvt_pk_bf16_f32 v53, v10, v11
	v_cvt_pk_bf16_f32 v54, v12, v13
	v_cvt_pk_bf16_f32 v55, v14, v15
	global_store_dwordx2 v19, v[48:49], s[12:13]
	global_store_dwordx2 v19, v[50:51], s[12:13] offset:512
	global_store_dwordx2 v19, v[52:53], s[12:13] offset:1024
	global_store_dwordx2 v19, v[54:55], s[12:13] offset:1536
	s_mov_b32 s6, s10
	s_mov_b32 s15, s11
	s_add_u32 s10, s6, s72
	s_cmp_lt_u32 s10, 0x4200
	s_cbranch_scc0 .Lpb_last_b
	s_mul_i32 s12, s15, 0x3000
	s_add_u32 s16, s2, s12
	s_addc_u32 s17, s3, 0
	s_add_u32 s0, s16, 0x1000
	s_addc_u32 s1, s17, 0
	global_load_dwordx4 v[96:99], v18, s[16:17]
	global_load_dwordx4 v[100:103], v18, s[16:17] offset:1024
	global_load_dwordx4 v[104:107], v18, s[16:17] offset:2048
	global_load_dwordx4 v[108:111], v18, s[16:17] offset:3072
	global_load_dwordx4 v[112:115], v18, s[0:1]
	global_load_dwordx4 v[116:119], v18, s[0:1] offset:1024
	global_load_dwordx4 v[120:123], v18, s[0:1] offset:2048
	global_load_dwordx4 v[124:127], v18, s[0:1] offset:3072
	s_cmp_ge_u32 s10, 0x2100
	s_cselect_b32 s12, 1, 0
	s_mul_i32 s13, s12, 0x2100
	s_sub_u32 s13, s10, s13
	s_lshl_b32 s14, s12, 13
	s_add_u32 s14, s14, s13
	s_lshl_b32 s8, s12, 8
	s_add_u32 s8, s8, s13
	s_sub_u32 s8, s8, 0x2000
	s_cmp_lt_u32 s13, 0x2000
	s_cselect_b32 s14, s14, s8
	s_cselect_b32 s11, s12, 2
	s_cselect_b32 s8, s52, s56
	s_cselect_b32 s9, s53, s57
	s_lshl_b32 s14, s14, 12
	s_add_u32 s8, s8, s14
	s_addc_u32 s9, s9, 0
	global_load_dwordx4 v[64:67], v18, s[8:9]
	global_load_dwordx4 v[68:71], v18, s[8:9] offset:1024
	global_load_dwordx4 v[72:75], v18, s[8:9] offset:2048
	global_load_dwordx4 v[76:79], v18, s[8:9] offset:3072
	s_waitcnt vmcnt(12)
	v_add_f32_e32 v38, v80, v81
	v_add_f32_e32 v39, v82, v83
	v_add_f32_e32 v40, v84, v85
	v_add_f32_e32 v41, v86, v87
	v_add_f32_e32 v42, v88, v89
	v_add_f32_e32 v43, v90, v91
	v_add_f32_e32 v44, v92, v93
	v_add_f32_e32 v45, v94, v95
	v_add_f32_e32 v38, v38, v39
	v_add_f32_e32 v40, v40, v41
	v_add_f32_e32 v42, v42, v43
	v_add_f32_e32 v44, v44, v45
	v_add_f32_e32 v38, v38, v40
	v_add_f32_e32 v38, v38, v42
	v_add_f32_e32 v38, v38, v44
	ds_bpermute_b32 v46, v29, v38
	s_waitcnt lgkmcnt(0)
	v_add_f32_e32 v38, v38, v46
	ds_bpermute_b32 v46, v30, v38
	s_waitcnt lgkmcnt(0)
	v_add_f32_e32 v38, v38, v46
	ds_bpermute_b32 v46, v31, v38
	s_waitcnt lgkmcnt(0)
	v_add_f32_e32 v38, v38, v46
	ds_bpermute_b32 v46, v32, v38
	s_waitcnt lgkmcnt(0)
	v_add_f32_e32 v38, v38, v46
	ds_bpermute_b32 v46, v33, v38
	s_waitcnt lgkmcnt(0)
	v_add_f32_e32 v38, v38, v46
	ds_bpermute_b32 v46, v34, v38
	s_waitcnt lgkmcnt(0)
	v_add_f32_e32 v38, v38, v46
	v_fmamk_f32 v0, v38, 0xba800000, v80
	v_fmamk_f32 v1, v38, 0xba800000, v81
	v_fmamk_f32 v2, v38, 0xba800000, v82
	v_fmamk_f32 v3, v38, 0xba800000, v83
	v_fmamk_f32 v4, v38, 0xba800000, v84
	v_fmamk_f32 v5, v38, 0xba800000, v85
	v_fmamk_f32 v6, v38, 0xba800000, v86
	v_fmamk_f32 v7, v38, 0xba800000, v87
	v_fmamk_f32 v8, v38, 0xba800000, v88
	v_fmamk_f32 v9, v38, 0xba800000, v89
	v_fmamk_f32 v10, v38, 0xba800000, v90
	v_fmamk_f32 v11, v38, 0xba800000, v91
	v_fmamk_f32 v12, v38, 0xba800000, v92
	v_fmamk_f32 v13, v38, 0xba800000, v93
	v_fmamk_f32 v14, v38, 0xba800000, v94
	v_fmamk_f32 v15, v38, 0xba800000, v95
	v_mul_f32_e32 v38, v0, v0
	v_mul_f32_e32 v39, v2, v2
	v_mul_f32_e32 v40, v4, v4
	v_mul_f32_e32 v41, v6, v6
	v_mul_f32_e32 v42, v8, v8
	v_mul_f32_e32 v43, v10, v10
	v_mul_f32_e32 v44, v12, v12
	v_mul_f32_e32 v45, v14, v14
	v_fmac_f32_e32 v38, v1, v1
	v_fmac_f32_e32 v39, v3, v3
	v_fmac_f32_e32 v40, v5, v5
	v_fmac_f32_e32 v41, v7, v7
	v_fmac_f32_e32 v42, v9, v9
	v_fmac_f32_e32 v43, v11, v11
	v_fmac_f32_e32 v44, v13, v13
	v_fmac_f32_e32 v45, v15, v15
	v_add_f32_e32 v38, v38, v39
	v_add_f32_e32 v40, v40, v41
	v_add_f32_e32 v42, v42, v43
	v_add_f32_e32 v44, v44, v45
	v_add_f32_e32 v38, v38, v40
	v_add_f32_e32 v38, v38, v42
	v_add_f32_e32 v38, v38, v44
	ds_bpermute_b32 v46, v29, v38
	s_waitcnt lgkmcnt(0)
	v_add_f32_e32 v38, v38, v46
	ds_bpermute_b32 v46, v30, v38
	s_waitcnt lgkmcnt(0)
	v_add_f32_e32 v38, v38, v46
	ds_bpermute_b32 v46, v31, v38
	s_waitcnt lgkmcnt(0)
	v_add_f32_e32 v38, v38, v46
	ds_bpermute_b32 v46, v32, v38
	s_waitcnt lgkmcnt(0)
	v_add_f32_e32 v38, v38, v46
	ds_bpermute_b32 v46, v33, v38
	s_waitcnt lgkmcnt(0)
	v_add_f32_e32 v38, v38, v46
	ds_bpermute_b32 v46, v34, v38
	s_waitcnt lgkmcnt(0)
	v_add_f32_e32 v38, v38, v46
	v_fmamk_f32 v56, v38, 0x3a800000, v36
	v_mul_f32_e32 v57, 0x4f800000, v56
	v_cmp_gt_f32_e32 vcc, s7, v56
	s_nop 1
	v_cndmask_b32_e32 v58, v56, v57, vcc
	v_sqrt_f32_e32 v59, v58
	s_nop 0
	v_add_u32_e32 v60, -1, v59
	v_add_u32_e32 v61, 1, v59
	v_fma_f32 v62, -v60, v59, v58
	v_fma_f32 v63, -v61, v59, v58
	v_cmp_ge_f32_e64 s[12:13], 0, v62
	s_nop 1
	v_cndmask_b32_e64 v60, v59, v60, s[12:13]
	v_cmp_lt_f32_e64 s[12:13], 0, v63
	s_nop 1
	v_cndmask_b32_e64 v60, v60, v61, s[12:13]
	v_mul_f32_e32 v61, 0x37800000, v60
	v_cndmask_b32_e32 v60, v60, v61, vcc
	v_cmp_class_f32_e32 vcc, v58, v37
	s_nop 1
	v_cndmask_b32_e32 v58, v60, v58, vcc
	v_div_scale_f32 v60, s[12:13], v58, v58, 1.0
	v_rcp_f32_e32 v61, v60
	v_div_scale_f32 v59, vcc, 1.0, v58, 1.0
	v_fma_f32 v62, -v60, v61, 1.0
	v_fmac_f32_e32 v61, v62, v61
	v_mul_f32_e32 v62, v59, v61
	v_fma_f32 v63, -v60, v62, v59
	v_fmac_f32_e32 v62, v63, v61
	v_fma_f32 v60, -v60, v62, v59
	v_div_fmas_f32 v60, v60, v61, v62
	v_div_fixup_f32 v60, v60, v58, 1.0
	s_lshl_b32 s12, s6, 11
	s_add_u32 s12, s2, s12
	s_addc_u32 s13, s3, 0
	s_add_u32 s12, s12, 0x5b00000
	s_addc_u32 s13, s13, 0
	v_mul_f32_e32 v0, v0, v60
	v_mul_f32_e32 v1, v1, v60
	v_mul_f32_e32 v2, v2, v60
	v_mul_f32_e32 v3, v3, v60
	v_mul_f32_e32 v4, v4, v60
	v_mul_f32_e32 v5, v5, v60
	v_mul_f32_e32 v6, v6, v60
	v_mul_f32_e32 v7, v7, v60
	v_mul_f32_e32 v8, v8, v60
	v_mul_f32_e32 v9, v9, v60
	v_mul_f32_e32 v10, v10, v60
	v_mul_f32_e32 v11, v11, v60
	v_mul_f32_e32 v12, v12, v60
	v_mul_f32_e32 v13, v13, v60
	v_mul_f32_e32 v14, v14, v60
	v_mul_f32_e32 v15, v15, v60
	s_waitcnt vmcnt(4)
	v_add_f32_e32 v112, 1.0, v112
	v_add_f32_e32 v113, 1.0, v113
	v_add_f32_e32 v114, 1.0, v114
	v_add_f32_e32 v115, 1.0, v115
	v_add_f32_e32 v116, 1.0, v116
	v_add_f32_e32 v117, 1.0, v117
	v_add_f32_e32 v118, 1.0, v118
	v_add_f32_e32 v119, 1.0, v119
	v_add_f32_e32 v120, 1.0, v120
	v_add_f32_e32 v121, 1.0, v121
	v_add_f32_e32 v122, 1.0, v122
	v_add_f32_e32 v123, 1.0, v123
	v_add_f32_e32 v124, 1.0, v124
	v_add_f32_e32 v125, 1.0, v125
	v_add_f32_e32 v126, 1.0, v126
	v_add_f32_e32 v127, 1.0, v127
	v_fma_f32 v0, v0, v112, v96
	v_fma_f32 v1, v1, v113, v97
	v_fma_f32 v2, v2, v114, v98
	v_fma_f32 v3, v3, v115, v99
	v_fma_f32 v4, v4, v116, v100
	v_fma_f32 v5, v5, v117, v101
	v_fma_f32 v6, v6, v118, v102
	v_fma_f32 v7, v7, v119, v103
	v_fma_f32 v8, v8, v120, v104
	v_fma_f32 v9, v9, v121, v105
	v_fma_f32 v10, v10, v122, v106
	v_fma_f32 v11, v11, v123, v107
	v_fma_f32 v12, v12, v124, v108
	v_fma_f32 v13, v13, v125, v109
	v_fma_f32 v14, v14, v126, v110
	v_fma_f32 v15, v15, v127, v111
	v_cvt_pk_bf16_f32 v48, v0, v1
	v_cvt_pk_bf16_f32 v49, v2, v3
	v_cvt_pk_bf16_f32 v50, v4, v5
	v_cvt_pk_bf16_f32 v51, v6, v7
	v_cvt_pk_bf16_f32 v52, v8, v9
	v_cvt_pk_bf16_f32 v53, v10, v11
	v_cvt_pk_bf16_f32 v54, v12, v13
	v_cvt_pk_bf16_f32 v55, v14, v15
	global_store_dwordx2 v19, v[48:49], s[12:13]
	global_store_dwordx2 v19, v[50:51], s[12:13] offset:512
	global_store_dwordx2 v19, v[52:53], s[12:13] offset:1024
	global_store_dwordx2 v19, v[54:55], s[12:13] offset:1536
	s_mov_b32 s6, s10
	s_mov_b32 s15, s11
	s_branch .Lpb_loop
.Lpb_last_a:
	s_mul_i32 s12, s15, 0x3000
	s_add_u32 s16, s2, s12
	s_addc_u32 s17, s3, 0
	s_add_u32 s0, s16, 0x1000
	s_addc_u32 s1, s17, 0
	global_load_dwordx4 v[96:99], v18, s[16:17]
	global_load_dwordx4 v[100:103], v18, s[16:17] offset:1024
	global_load_dwordx4 v[104:107], v18, s[16:17] offset:2048
	global_load_dwordx4 v[108:111], v18, s[16:17] offset:3072
	global_load_dwordx4 v[112:115], v18, s[0:1]
	global_load_dwordx4 v[116:119], v18, s[0:1] offset:1024
	global_load_dwordx4 v[120:123], v18, s[0:1] offset:2048
	global_load_dwordx4 v[124:127], v18, s[0:1] offset:3072
	s_waitcnt vmcnt(8)
	v_add_f32_e32 v38, v64, v65
	v_add_f32_e32 v39, v66, v67
	v_add_f32_e32 v40, v68, v69
	v_add_f32_e32 v41, v70, v71
	v_add_f32_e32 v42, v72, v73
	v_add_f32_e32 v43, v74, v75
	v_add_f32_e32 v44, v76, v77
	v_add_f32_e32 v45, v78, v79
	v_add_f32_e32 v38, v38, v39
	v_add_f32_e32 v40, v40, v41
	v_add_f32_e32 v42, v42, v43
	v_add_f32_e32 v44, v44, v45
	v_add_f32_e32 v38, v38, v40
	v_add_f32_e32 v38, v38, v42
	v_add_f32_e32 v38, v38, v44
	ds_bpermute_b32 v46, v29, v38
	s_waitcnt lgkmcnt(0)
	v_add_f32_e32 v38, v38, v46
	ds_bpermute_b32 v46, v30, v38
	s_waitcnt lgkmcnt(0)
	v_add_f32_e32 v38, v38, v46
	ds_bpermute_b32 v46, v31, v38
	s_waitcnt lgkmcnt(0)
	v_add_f32_e32 v38, v38, v46
	ds_bpermute_b32 v46, v32, v38
	s_waitcnt lgkmcnt(0)
	v_add_f32_e32 v38, v38, v46
	ds_bpermute_b32 v46, v33, v38
	s_waitcnt lgkmcnt(0)
	v_add_f32_e32 v38, v38, v46
	ds_bpermute_b32 v46, v34, v38
	s_waitcnt lgkmcnt(0)
	v_add_f32_e32 v38, v38, v46
	v_fmamk_f32 v0, v38, 0xba800000, v64
	v_fmamk_f32 v1, v38, 0xba800000, v65
	v_fmamk_f32 v2, v38, 0xba800000, v66
	v_fmamk_f32 v3, v38, 0xba800000, v67
	v_fmamk_f32 v4, v38, 0xba800000, v68
	v_fmamk_f32 v5, v38, 0xba800000, v69
	v_fmamk_f32 v6, v38, 0xba800000, v70
	v_fmamk_f32 v7, v38, 0xba800000, v71
	v_fmamk_f32 v8, v38, 0xba800000, v72
	v_fmamk_f32 v9, v38, 0xba800000, v73
	v_fmamk_f32 v10, v38, 0xba800000, v74
	v_fmamk_f32 v11, v38, 0xba800000, v75
	v_fmamk_f32 v12, v38, 0xba800000, v76
	v_fmamk_f32 v13, v38, 0xba800000, v77
	v_fmamk_f32 v14, v38, 0xba800000, v78
	v_fmamk_f32 v15, v38, 0xba800000, v79
	v_mul_f32_e32 v38, v0, v0
	v_mul_f32_e32 v39, v2, v2
	v_mul_f32_e32 v40, v4, v4
	v_mul_f32_e32 v41, v6, v6
	v_mul_f32_e32 v42, v8, v8
	v_mul_f32_e32 v43, v10, v10
	v_mul_f32_e32 v44, v12, v12
	v_mul_f32_e32 v45, v14, v14
	v_fmac_f32_e32 v38, v1, v1
	v_fmac_f32_e32 v39, v3, v3
	v_fmac_f32_e32 v40, v5, v5
	v_fmac_f32_e32 v41, v7, v7
	v_fmac_f32_e32 v42, v9, v9
	v_fmac_f32_e32 v43, v11, v11
	v_fmac_f32_e32 v44, v13, v13
	v_fmac_f32_e32 v45, v15, v15
	v_add_f32_e32 v38, v38, v39
	v_add_f32_e32 v40, v40, v41
	v_add_f32_e32 v42, v42, v43
	v_add_f32_e32 v44, v44, v45
	v_add_f32_e32 v38, v38, v40
	v_add_f32_e32 v38, v38, v42
	v_add_f32_e32 v38, v38, v44
	ds_bpermute_b32 v46, v29, v38
	s_waitcnt lgkmcnt(0)
	v_add_f32_e32 v38, v38, v46
	ds_bpermute_b32 v46, v30, v38
	s_waitcnt lgkmcnt(0)
	v_add_f32_e32 v38, v38, v46
	ds_bpermute_b32 v46, v31, v38
	s_waitcnt lgkmcnt(0)
	v_add_f32_e32 v38, v38, v46
	ds_bpermute_b32 v46, v32, v38
	s_waitcnt lgkmcnt(0)
	v_add_f32_e32 v38, v38, v46
	ds_bpermute_b32 v46, v33, v38
	s_waitcnt lgkmcnt(0)
	v_add_f32_e32 v38, v38, v46
	ds_bpermute_b32 v46, v34, v38
	s_waitcnt lgkmcnt(0)
	v_add_f32_e32 v38, v38, v46
	v_fmamk_f32 v56, v38, 0x3a800000, v36
	v_mul_f32_e32 v57, 0x4f800000, v56
	v_cmp_gt_f32_e32 vcc, s7, v56
	s_nop 1
	v_cndmask_b32_e32 v58, v56, v57, vcc
	v_sqrt_f32_e32 v59, v58
	s_nop 0
	v_add_u32_e32 v60, -1, v59
	v_add_u32_e32 v61, 1, v59
	v_fma_f32 v62, -v60, v59, v58
	v_fma_f32 v63, -v61, v59, v58
	v_cmp_ge_f32_e64 s[12:13], 0, v62
	s_nop 1
	v_cndmask_b32_e64 v60, v59, v60, s[12:13]
	v_cmp_lt_f32_e64 s[12:13], 0, v63
	s_nop 1
	v_cndmask_b32_e64 v60, v60, v61, s[12:13]
	v_mul_f32_e32 v61, 0x37800000, v60
	v_cndmask_b32_e32 v60, v60, v61, vcc
	v_cmp_class_f32_e32 vcc, v58, v37
	s_nop 1
	v_cndmask_b32_e32 v58, v60, v58, vcc
	v_div_scale_f32 v60, s[12:13], v58, v58, 1.0
	v_rcp_f32_e32 v61, v60
	v_div_scale_f32 v59, vcc, 1.0, v58, 1.0
	v_fma_f32 v62, -v60, v61, 1.0
	v_fmac_f32_e32 v61, v62, v61
	v_mul_f32_e32 v62, v59, v61
	v_fma_f32 v63, -v60, v62, v59
	v_fmac_f32_e32 v62, v63, v61
	v_fma_f32 v60, -v60, v62, v59
	v_div_fmas_f32 v60, v60, v61, v62
	v_div_fixup_f32 v60, v60, v58, 1.0
	s_lshl_b32 s12, s6, 11
	s_add_u32 s12, s2, s12
	s_addc_u32 s13, s3, 0
	s_add_u32 s12, s12, 0x5b00000
	s_addc_u32 s13, s13, 0
	v_mul_f32_e32 v0, v0, v60
	v_mul_f32_e32 v1, v1, v60
	v_mul_f32_e32 v2, v2, v60
	v_mul_f32_e32 v3, v3, v60
	v_mul_f32_e32 v4, v4, v60
	v_mul_f32_e32 v5, v5, v60
	v_mul_f32_e32 v6, v6, v60
	v_mul_f32_e32 v7, v7, v60
	v_mul_f32_e32 v8, v8, v60
	v_mul_f32_e32 v9, v9, v60
	v_mul_f32_e32 v10, v10, v60
	v_mul_f32_e32 v11, v11, v60
	v_mul_f32_e32 v12, v12, v60
	v_mul_f32_e32 v13, v13, v60
	v_mul_f32_e32 v14, v14, v60
	v_mul_f32_e32 v15, v15, v60
	s_waitcnt vmcnt(0)
	v_add_f32_e32 v112, 1.0, v112
	v_add_f32_e32 v113, 1.0, v113
	v_add_f32_e32 v114, 1.0, v114
	v_add_f32_e32 v115, 1.0, v115
	v_add_f32_e32 v116, 1.0, v116
	v_add_f32_e32 v117, 1.0, v117
	v_add_f32_e32 v118, 1.0, v118
	v_add_f32_e32 v119, 1.0, v119
	v_add_f32_e32 v120, 1.0, v120
	v_add_f32_e32 v121, 1.0, v121
	v_add_f32_e32 v122, 1.0, v122
	v_add_f32_e32 v123, 1.0, v123
	v_add_f32_e32 v124, 1.0, v124
	v_add_f32_e32 v125, 1.0, v125
	v_add_f32_e32 v126, 1.0, v126
	v_add_f32_e32 v127, 1.0, v127
	v_fma_f32 v0, v0, v112, v96
	v_fma_f32 v1, v1, v113, v97
	v_fma_f32 v2, v2, v114, v98
	v_fma_f32 v3, v3, v115, v99
	v_fma_f32 v4, v4, v116, v100
	v_fma_f32 v5, v5, v117, v101
	v_fma_f32 v6, v6, v118, v102
	v_fma_f32 v7, v7, v119, v103
	v_fma_f32 v8, v8, v120, v104
	v_fma_f32 v9, v9, v121, v105
	v_fma_f32 v10, v10, v122, v106
	v_fma_f32 v11, v11, v123, v107
	v_fma_f32 v12, v12, v124, v108
	v_fma_f32 v13, v13, v125, v109
	v_fma_f32 v14, v14, v126, v110
	v_fma_f32 v15, v15, v127, v111
	v_cvt_pk_bf16_f32 v48, v0, v1
	v_cvt_pk_bf16_f32 v49, v2, v3
	v_cvt_pk_bf16_f32 v50, v4, v5
	v_cvt_pk_bf16_f32 v51, v6, v7
	v_cvt_pk_bf16_f32 v52, v8, v9
	v_cvt_pk_bf16_f32 v53, v10, v11
	v_cvt_pk_bf16_f32 v54, v12, v13
	v_cvt_pk_bf16_f32 v55, v14, v15
	global_store_dwordx2 v19, v[48:49], s[12:13]
	global_store_dwordx2 v19, v[50:51], s[12:13] offset:512
	global_store_dwordx2 v19, v[52:53], s[12:13] offset:1024
	global_store_dwordx2 v19, v[54:55], s[12:13] offset:1536
	s_branch .Lpb_done
.Lpb_last_b:
	s_mul_i32 s12, s15, 0x3000
	s_add_u32 s16, s2, s12
	s_addc_u32 s17, s3, 0
	s_add_u32 s0, s16, 0x1000
	s_addc_u32 s1, s17, 0
	global_load_dwordx4 v[96:99], v18, s[16:17]
	global_load_dwordx4 v[100:103], v18, s[16:17] offset:1024
	global_load_dwordx4 v[104:107], v18, s[16:17] offset:2048
	global_load_dwordx4 v[108:111], v18, s[16:17] offset:3072
	global_load_dwordx4 v[112:115], v18, s[0:1]
	global_load_dwordx4 v[116:119], v18, s[0:1] offset:1024
	global_load_dwordx4 v[120:123], v18, s[0:1] offset:2048
	global_load_dwordx4 v[124:127], v18, s[0:1] offset:3072
	s_waitcnt vmcnt(8)
	v_add_f32_e32 v38, v80, v81
	v_add_f32_e32 v39, v82, v83
	v_add_f32_e32 v40, v84, v85
	v_add_f32_e32 v41, v86, v87
	v_add_f32_e32 v42, v88, v89
	v_add_f32_e32 v43, v90, v91
	v_add_f32_e32 v44, v92, v93
	v_add_f32_e32 v45, v94, v95
	v_add_f32_e32 v38, v38, v39
	v_add_f32_e32 v40, v40, v41
	v_add_f32_e32 v42, v42, v43
	v_add_f32_e32 v44, v44, v45
	v_add_f32_e32 v38, v38, v40
	v_add_f32_e32 v38, v38, v42
	v_add_f32_e32 v38, v38, v44
	ds_bpermute_b32 v46, v29, v38
	s_waitcnt lgkmcnt(0)
	v_add_f32_e32 v38, v38, v46
	ds_bpermute_b32 v46, v30, v38
	s_waitcnt lgkmcnt(0)
	v_add_f32_e32 v38, v38, v46
	ds_bpermute_b32 v46, v31, v38
	s_waitcnt lgkmcnt(0)
	v_add_f32_e32 v38, v38, v46
	ds_bpermute_b32 v46, v32, v38
	s_waitcnt lgkmcnt(0)
	v_add_f32_e32 v38, v38, v46
	ds_bpermute_b32 v46, v33, v38
	s_waitcnt lgkmcnt(0)
	v_add_f32_e32 v38, v38, v46
	ds_bpermute_b32 v46, v34, v38
	s_waitcnt lgkmcnt(0)
	v_add_f32_e32 v38, v38, v46
	v_fmamk_f32 v0, v38, 0xba800000, v80
	v_fmamk_f32 v1, v38, 0xba800000, v81
	v_fmamk_f32 v2, v38, 0xba800000, v82
	v_fmamk_f32 v3, v38, 0xba800000, v83
	v_fmamk_f32 v4, v38, 0xba800000, v84
	v_fmamk_f32 v5, v38, 0xba800000, v85
	v_fmamk_f32 v6, v38, 0xba800000, v86
	v_fmamk_f32 v7, v38, 0xba800000, v87
	v_fmamk_f32 v8, v38, 0xba800000, v88
	v_fmamk_f32 v9, v38, 0xba800000, v89
	v_fmamk_f32 v10, v38, 0xba800000, v90
	v_fmamk_f32 v11, v38, 0xba800000, v91
	v_fmamk_f32 v12, v38, 0xba800000, v92
	v_fmamk_f32 v13, v38, 0xba800000, v93
	v_fmamk_f32 v14, v38, 0xba800000, v94
	v_fmamk_f32 v15, v38, 0xba800000, v95
	v_mul_f32_e32 v38, v0, v0
	v_mul_f32_e32 v39, v2, v2
	v_mul_f32_e32 v40, v4, v4
	v_mul_f32_e32 v41, v6, v6
	v_mul_f32_e32 v42, v8, v8
	v_mul_f32_e32 v43, v10, v10
	v_mul_f32_e32 v44, v12, v12
	v_mul_f32_e32 v45, v14, v14
	v_fmac_f32_e32 v38, v1, v1
	v_fmac_f32_e32 v39, v3, v3
	v_fmac_f32_e32 v40, v5, v5
	v_fmac_f32_e32 v41, v7, v7
	v_fmac_f32_e32 v42, v9, v9
	v_fmac_f32_e32 v43, v11, v11
	v_fmac_f32_e32 v44, v13, v13
	v_fmac_f32_e32 v45, v15, v15
	v_add_f32_e32 v38, v38, v39
	v_add_f32_e32 v40, v40, v41
	v_add_f32_e32 v42, v42, v43
	v_add_f32_e32 v44, v44, v45
	v_add_f32_e32 v38, v38, v40
	v_add_f32_e32 v38, v38, v42
	v_add_f32_e32 v38, v38, v44
	ds_bpermute_b32 v46, v29, v38
	s_waitcnt lgkmcnt(0)
	v_add_f32_e32 v38, v38, v46
	ds_bpermute_b32 v46, v30, v38
	s_waitcnt lgkmcnt(0)
	v_add_f32_e32 v38, v38, v46
	ds_bpermute_b32 v46, v31, v38
	s_waitcnt lgkmcnt(0)
	v_add_f32_e32 v38, v38, v46
	ds_bpermute_b32 v46, v32, v38
	s_waitcnt lgkmcnt(0)
	v_add_f32_e32 v38, v38, v46
	ds_bpermute_b32 v46, v33, v38
	s_waitcnt lgkmcnt(0)
	v_add_f32_e32 v38, v38, v46
	ds_bpermute_b32 v46, v34, v38
	s_waitcnt lgkmcnt(0)
	v_add_f32_e32 v38, v38, v46
	v_fmamk_f32 v56, v38, 0x3a800000, v36
	v_mul_f32_e32 v57, 0x4f800000, v56
	v_cmp_gt_f32_e32 vcc, s7, v56
	s_nop 1
	v_cndmask_b32_e32 v58, v56, v57, vcc
	v_sqrt_f32_e32 v59, v58
	s_nop 0
	v_add_u32_e32 v60, -1, v59
	v_add_u32_e32 v61, 1, v59
	v_fma_f32 v62, -v60, v59, v58
	v_fma_f32 v63, -v61, v59, v58
	v_cmp_ge_f32_e64 s[12:13], 0, v62
	s_nop 1
	v_cndmask_b32_e64 v60, v59, v60, s[12:13]
	v_cmp_lt_f32_e64 s[12:13], 0, v63
	s_nop 1
	v_cndmask_b32_e64 v60, v60, v61, s[12:13]
	v_mul_f32_e32 v61, 0x37800000, v60
	v_cndmask_b32_e32 v60, v60, v61, vcc
	v_cmp_class_f32_e32 vcc, v58, v37
	s_nop 1
	v_cndmask_b32_e32 v58, v60, v58, vcc
	v_div_scale_f32 v60, s[12:13], v58, v58, 1.0
	v_rcp_f32_e32 v61, v60
	v_div_scale_f32 v59, vcc, 1.0, v58, 1.0
	v_fma_f32 v62, -v60, v61, 1.0
	v_fmac_f32_e32 v61, v62, v61
	v_mul_f32_e32 v62, v59, v61
	v_fma_f32 v63, -v60, v62, v59
	v_fmac_f32_e32 v62, v63, v61
	v_fma_f32 v60, -v60, v62, v59
	v_div_fmas_f32 v60, v60, v61, v62
	v_div_fixup_f32 v60, v60, v58, 1.0
	s_lshl_b32 s12, s6, 11
	s_add_u32 s12, s2, s12
	s_addc_u32 s13, s3, 0
	s_add_u32 s12, s12, 0x5b00000
	s_addc_u32 s13, s13, 0
	v_mul_f32_e32 v0, v0, v60
	v_mul_f32_e32 v1, v1, v60
	v_mul_f32_e32 v2, v2, v60
	v_mul_f32_e32 v3, v3, v60
	v_mul_f32_e32 v4, v4, v60
	v_mul_f32_e32 v5, v5, v60
	v_mul_f32_e32 v6, v6, v60
	v_mul_f32_e32 v7, v7, v60
	v_mul_f32_e32 v8, v8, v60
	v_mul_f32_e32 v9, v9, v60
	v_mul_f32_e32 v10, v10, v60
	v_mul_f32_e32 v11, v11, v60
	v_mul_f32_e32 v12, v12, v60
	v_mul_f32_e32 v13, v13, v60
	v_mul_f32_e32 v14, v14, v60
	v_mul_f32_e32 v15, v15, v60
	s_waitcnt vmcnt(0)
	v_add_f32_e32 v112, 1.0, v112
	v_add_f32_e32 v113, 1.0, v113
	v_add_f32_e32 v114, 1.0, v114
	v_add_f32_e32 v115, 1.0, v115
	v_add_f32_e32 v116, 1.0, v116
	v_add_f32_e32 v117, 1.0, v117
	v_add_f32_e32 v118, 1.0, v118
	v_add_f32_e32 v119, 1.0, v119
	v_add_f32_e32 v120, 1.0, v120
	v_add_f32_e32 v121, 1.0, v121
	v_add_f32_e32 v122, 1.0, v122
	v_add_f32_e32 v123, 1.0, v123
	v_add_f32_e32 v124, 1.0, v124
	v_add_f32_e32 v125, 1.0, v125
	v_add_f32_e32 v126, 1.0, v126
	v_add_f32_e32 v127, 1.0, v127
	v_fma_f32 v0, v0, v112, v96
	v_fma_f32 v1, v1, v113, v97
	v_fma_f32 v2, v2, v114, v98
	v_fma_f32 v3, v3, v115, v99
	v_fma_f32 v4, v4, v116, v100
	v_fma_f32 v5, v5, v117, v101
	v_fma_f32 v6, v6, v118, v102
	v_fma_f32 v7, v7, v119, v103
	v_fma_f32 v8, v8, v120, v104
	v_fma_f32 v9, v9, v121, v105
	v_fma_f32 v10, v10, v122, v106
	v_fma_f32 v11, v11, v123, v107
	v_fma_f32 v12, v12, v124, v108
	v_fma_f32 v13, v13, v125, v109
	v_fma_f32 v14, v14, v126, v110
	v_fma_f32 v15, v15, v127, v111
	v_cvt_pk_bf16_f32 v48, v0, v1
	v_cvt_pk_bf16_f32 v49, v2, v3
	v_cvt_pk_bf16_f32 v50, v4, v5
	v_cvt_pk_bf16_f32 v51, v6, v7
	v_cvt_pk_bf16_f32 v52, v8, v9
	v_cvt_pk_bf16_f32 v53, v10, v11
	v_cvt_pk_bf16_f32 v54, v12, v13
	v_cvt_pk_bf16_f32 v55, v14, v15
	global_store_dwordx2 v19, v[48:49], s[12:13]
	global_store_dwordx2 v19, v[50:51], s[12:13] offset:512
	global_store_dwordx2 v19, v[52:53], s[12:13] offset:1024
	global_store_dwordx2 v19, v[54:55], s[12:13] offset:1536
.Lpb_done:
.LBB0_164:
	s_or_b64 exec, exec, s[4:5]
	s_waitcnt vmcnt(0)
	s_waitcnt lgkmcnt(0)
	s_barrier
	s_mov_b64 s[30:31], exec
	v_readlane_b32 s0, v253, 6
	v_readlane_b32 s1, v253, 7
	s_and_b64 s[0:1], s[30:31], s[0:1]
	s_mov_b64 exec, s[0:1]
	s_cbranch_execz .LBB0_208
	v_readlane_b32 s34, v254, 3
	s_add_i32 s0, 0, 0x25ff0
	v_readlane_b32 s35, v254, 4
	s_mov_b32 s36, s70
	v_mov_b32_e32 v0, s0
	s_waitcnt vmcnt(0) expcnt(0) lgkmcnt(0)
	ds_read_b32 v2, v0
	s_add_i32 s0, 0, 0x25ff4
	v_mov_b32_e32 v0, s0
	ds_read_b32 v0, v0
	s_waitcnt lgkmcnt(1)
	v_cmp_ne_u32_e32 vcc, 0, v2
	s_cbranch_vccnz .LBB0_179
	s_add_u32 s2, s34, 0x1000
	s_addc_u32 s3, s35, 0
	s_add_u32 s4, s34, 0x1100
	s_addc_u32 s5, s35, 0
	s_add_u32 s6, s34, 0x1200
	s_addc_u32 s7, s35, 0
	s_add_u32 s8, s34, 0x1300
	s_mul_i32 s18, s97, s33
	s_addc_u32 s9, s35, 0
	s_mul_i32 s18, s18, s96
	s_mov_b32 s19, 1
	s_mov_b64 s[0:1], 0
	s_waitcnt lgkmcnt(0)
	v_mov_b64_e32 v[0:1], s[34:35]
	v_mov_b64_e32 v[2:3], s[2:3]
	v_mov_b64_e32 v[4:5], s[4:5]
	v_mov_b64_e32 v[6:7], s[6:7]
	v_mov_b64_e32 v[8:9], s[8:9]
	s_branch .LBB0_169
